# combo: wbl2 skip + single-counter barrier + epilogue rowsum preload + de-serialized in-proj weight loads
# speedup vs baseline: 1.0018x; 1.0018x over previous
; #define LAS __attribute__((address_space(3)))
; __device__ __forceinline__ void tr_item(const float* W, int K, int N, const float* kscale, bf16* WT, int dst_row0, LAS float* scr, int k0, int n0, int lane) {
;     const int n4 = 4 * (lane & 7); const bool ok = (n0 + n4) < N;
; #pragma unroll
;     for (int i = 0; i < 8; ++i) { const int kk = 8 * i + (lane >> 3); f32x4 v = ok ? *(const f32x4*)(W + (size_t)(k0 + kk) * N + n0 + n4) : (f32x4){0.f, 0.f, 0.f, 0.f}; if (kscale) v = v * kscale[k0 + kk];
;         scr[kk * 33 + n4] = v[0]; scr[kk * 33 + n4 + 1] = v[1]; scr[kk * 33 + n4 + 2] = v[2]; scr[kk * 33 + n4 + 3] = v[3]; }
; __device__ __forceinline__ void prologue(const Args& a, LAS unsigned char* lds, int wave, int lane) {
;     ...
;         if (r < I_WIN) {
;             const float* W = a.in[5] + (size_t)l * D * INCOLS; const float* ks = a.in[4] + (size_t)l * D;
;             const int nblk = NPROJ / 32, kb = r / nblk, nb = r % nblk;
;             tr_item(W, D, INCOLS, ks, (bf16*)(wl + WIN_OFF), 32 * nb, scr, 64 * kb, 32 * nb, lane);
.LBB0_20:
	s_andn2_b64 vcc, exec, s[2:3]
	s_cbranch_vccnz .LBB0_54
	s_mul_i32 s2, s68, 0xa10000
	s_mul_hi_i32 s0, s68, 0xa10000
	s_add_u32 s4, s46, s2
	s_addc_u32 s5, s47, s0
	s_add_i32 s0, s86, 0xdf00
	s_and_b32 s2, s0, 0xffff
	s_mul_i32 s2, s2, 0xba2f
	s_lshr_b32 s3, s2, 16
	s_lshr_b32 s2, s2, 22
	s_mulk_i32 s2, 0x58
	s_sub_i32 s0, s0, s2
	s_lshl_b32 s0, s0, 5
	s_and_b32 s0, s0, 0xffe0
	s_and_b32 s88, s3, 0xffc0
	s_lshl_b32 s70, s0, 2
	s_add_u32 s4, s4, s70
	v_or_b32_e32 v2, s0, v10
	s_addc_u32 s5, s5, 0
	v_cmp_gt_u32_e64 s[2:3], s80, v2
	v_lshl_add_u64 v[6:7], s[4:5], 0, v[14:15]
	v_mov_b32_e32 v2, v15
	v_mov_b32_e32 v3, v15
	v_mov_b32_e32 v4, v15
	v_mov_b32_e32 v5, v15
	v_mov_b32_e32 v42, v15
	v_mov_b32_e32 v43, v15
	v_mov_b32_e32 v44, v15
	v_mov_b32_e32 v45, v15
	v_mov_b32_e32 v46, v15
	v_mov_b32_e32 v47, v15
	v_mov_b32_e32 v48, v15
	v_mov_b32_e32 v49, v15
	v_mov_b32_e32 v50, v15
	v_mov_b32_e32 v51, v15
	v_mov_b32_e32 v52, v15
	v_mov_b32_e32 v53, v15
	v_mov_b32_e32 v54, v15
	v_mov_b32_e32 v55, v15
	v_mov_b32_e32 v56, v15
	v_mov_b32_e32 v57, v15
	v_mov_b32_e32 v58, v15
	v_mov_b32_e32 v59, v15
	v_mov_b32_e32 v60, v15
	v_mov_b32_e32 v61, v15
	v_mov_b32_e32 v62, v15
	v_mov_b32_e32 v63, v15
	v_mov_b32_e32 v64, v15
	v_mov_b32_e32 v65, v15
	v_mov_b32_e32 v66, v15
	v_mov_b32_e32 v67, v15
	v_mov_b32_e32 v68, v15
	v_mov_b32_e32 v69, v15
	v_mov_b32_e32 v71, v15
	v_or_b32_e32 v8, s88, v12
	s_and_saveexec_b64 s[4:5], s[2:3]
	s_cbranch_execz .Lwin_noload
	v_mul_u32_u24_e32 v70, 0xa10, v8
	v_lshlrev_b32_e32 v70, 2, v70
	v_lshl_add_u64 v[72:73], v[6:7], 0, v[70:71]
	global_load_dwordx4 v[2:5], v[72:73], off
	v_or_b32_e32 v70, s88, v1
	v_mul_u32_u24_e32 v70, 0xa10, v70
	v_lshlrev_b32_e32 v70, 2, v70
	v_lshl_add_u64 v[72:73], v[6:7], 0, v[70:71]
	global_load_dwordx4 v[42:45], v[72:73], off
	v_or_b32_e32 v70, s88, v11
	v_mul_u32_u24_e32 v70, 0xa10, v70
	v_lshlrev_b32_e32 v70, 2, v70
	v_lshl_add_u64 v[72:73], v[6:7], 0, v[70:71]
	global_load_dwordx4 v[46:49], v[72:73], off
	v_or_b32_e32 v70, s88, v20
	v_mul_u32_u24_e32 v70, 0xa10, v70
	v_lshlrev_b32_e32 v70, 2, v70
	v_lshl_add_u64 v[72:73], v[6:7], 0, v[70:71]
	global_load_dwordx4 v[50:53], v[72:73], off
	v_or_b32_e32 v70, s88, v21
	v_mul_u32_u24_e32 v70, 0xa10, v70
	v_lshlrev_b32_e32 v70, 2, v70
	v_lshl_add_u64 v[72:73], v[6:7], 0, v[70:71]
	global_load_dwordx4 v[54:57], v[72:73], off
	v_or_b32_e32 v70, s88, v22
	v_mul_u32_u24_e32 v70, 0xa10, v70
	v_lshlrev_b32_e32 v70, 2, v70
	v_lshl_add_u64 v[72:73], v[6:7], 0, v[70:71]
	global_load_dwordx4 v[58:61], v[72:73], off
	v_or_b32_e32 v70, s88, v23
	v_mul_u32_u24_e32 v70, 0xa10, v70
	v_lshlrev_b32_e32 v70, 2, v70
	v_lshl_add_u64 v[72:73], v[6:7], 0, v[70:71]
	global_load_dwordx4 v[62:65], v[72:73], off
	v_or_b32_e32 v70, s88, v24
	v_mul_u32_u24_e32 v70, 0xa10, v70
	v_lshlrev_b32_e32 v70, 2, v70
	v_lshl_add_u64 v[72:73], v[6:7], 0, v[70:71]
	global_load_dwordx4 v[66:69], v[72:73], off
.Lwin_noload:
	s_or_b64 exec, exec, s[4:5]
	s_lshl_b64 s[4:5], s[68:69], 12
	s_add_u32 s70, s44, s4
	v_cndmask_b32_e64 v9, 0, 1, s[64:65]
	s_addc_u32 s71, s45, s5
	v_cmp_ne_u32_e64 s[4:5], 1, v9
	s_andn2_b64 vcc, exec, s[64:65]
	s_cbranch_vccnz .Lwin_noscale
	v_add_lshl_u32 v70, v12, s88, 2
	global_load_dword v74, v70, s[70:71]
	global_load_dword v76, v70, s[70:71] offset:32
	global_load_dword v78, v70, s[70:71] offset:64
	global_load_dword v80, v70, s[70:71] offset:96
	global_load_dword v82, v70, s[70:71] offset:128
	global_load_dword v84, v70, s[70:71] offset:160
	global_load_dword v86, v70, s[70:71] offset:192
	global_load_dword v88, v70, s[70:71] offset:224
	s_waitcnt vmcnt(0)
	v_pk_mul_f32 v[4:5], v[4:5], v[74:75] op_sel_hi:[1,0]
	v_pk_mul_f32 v[2:3], v[2:3], v[74:75] op_sel_hi:[1,0]
	v_pk_mul_f32 v[44:45], v[44:45], v[76:77] op_sel_hi:[1,0]
	v_pk_mul_f32 v[42:43], v[42:43], v[76:77] op_sel_hi:[1,0]
	v_pk_mul_f32 v[48:49], v[48:49], v[78:79] op_sel_hi:[1,0]
	v_pk_mul_f32 v[46:47], v[46:47], v[78:79] op_sel_hi:[1,0]
	v_pk_mul_f32 v[52:53], v[52:53], v[80:81] op_sel_hi:[1,0]
	v_pk_mul_f32 v[50:51], v[50:51], v[80:81] op_sel_hi:[1,0]
	v_pk_mul_f32 v[56:57], v[56:57], v[82:83] op_sel_hi:[1,0]
	v_pk_mul_f32 v[54:55], v[54:55], v[82:83] op_sel_hi:[1,0]
	v_pk_mul_f32 v[60:61], v[60:61], v[84:85] op_sel_hi:[1,0]
	v_pk_mul_f32 v[58:59], v[58:59], v[84:85] op_sel_hi:[1,0]
	v_pk_mul_f32 v[64:65], v[64:65], v[86:87] op_sel_hi:[1,0]
	v_pk_mul_f32 v[62:63], v[62:63], v[86:87] op_sel_hi:[1,0]
	v_pk_mul_f32 v[68:69], v[68:69], v[88:89] op_sel_hi:[1,0]
	v_pk_mul_f32 v[66:67], v[66:67], v[88:89] op_sel_hi:[1,0]
; #define LAS __attribute__((address_space(3)))
; #define LDS_WAIT() asm volatile("s_waitcnt lgkmcnt(0)" ::: "memory")
; __device__ __forceinline__ unsigned pk2(float lo, float hi) { return f2bf(lo) | (f2bf(hi) << 16); }
; __device__ __forceinline__ void tr_item(const float* W, int K, int N, const float* kscale, bf16* WT, int dst_row0, LAS float* scr, int k0, int n0, int lane) {
;     ...
;     for (int i = 0; i < 8; ++i) { const int kk = 8 * i + (lane >> 3); f32x4 v = ok ? *(const f32x4*)(W + (size_t)(k0 + kk) * N + n0 + n4) : (f32x4){0.f, 0.f, 0.f, 0.f}; if (kscale) v = v * kscale[k0 + kk];
;         scr[kk * 33 + n4] = v[0]; scr[kk * 33 + n4 + 1] = v[1]; scr[kk * 33 + n4 + 2] = v[2]; scr[kk * 33 + n4 + 3] = v[3]; }
;     LDS_WAIT(); asm volatile("" ::: "memory");
;     const int c = lane & 7;
; #pragma unroll
;     for (int j = 0; j < 4; ++j) { const int n = (lane >> 3) + 8 * j; const LAS float* s = scr + (8 * c) * 33 + n;
;         u32x4 o; o.x = pk2(s[0 * 33], s[1 * 33]); o.y = pk2(s[2 * 33], s[3 * 33]); o.z = pk2(s[4 * 33], s[5 * 33]); o.w = pk2(s[6 * 33], s[7 * 33]);
;         *(u32x4*)(WT + (size_t)(dst_row0 + n) * K + k0 + 8 * c) = o; }
.Lwin_noscale:
	s_waitcnt vmcnt(0)
	ds_write2_b32 v26, v2, v3 offset1:1
	ds_write2_b32 v26, v4, v5 offset0:2 offset1:3
	ds_write2_b32 v27, v42, v43 offset1:1
	ds_write2_b32 v28, v44, v45 offset1:1
	ds_write2_b32 v29, v46, v47 offset1:1
	ds_write2_b32 v30, v48, v49 offset1:1
	ds_write2_b32 v31, v50, v51 offset1:1
	ds_write2_b32 v32, v52, v53 offset1:1
	ds_write2_b32 v33, v54, v55 offset1:1
	ds_write2_b32 v34, v56, v57 offset1:1
	ds_write2_b32 v35, v58, v59 offset1:1
	ds_write2_b32 v36, v60, v61 offset1:1
	ds_write2_b32 v37, v62, v63 offset1:1
	ds_write2_b32 v38, v64, v65 offset1:1
	ds_write2_b32 v39, v66, v67 offset1:1
	ds_write2_b32 v40, v68, v69 offset1:1
	s_waitcnt lgkmcnt(0)
	ds_read2_b32 v[6:7], v25 offset1:8
	s_lshl_b32 s2, s88, 1
	ds_read2_b32 v[18:19], v25 offset0:33 offset1:41
	s_add_u32 s2, s84, s2
	s_addc_u32 s3, s85, 0
	v_mov_b32_e32 v17, v15
	ds_read2_b32 v[42:43], v25 offset0:66 offset1:74
	v_lshl_add_u64 v[2:3], s[2:3], 0, v[16:17]
	ds_read2_b32 v[44:45], v25 offset0:99 offset1:107
	v_lshl_add_u64 v[8:9], v[2:3], 0, s[66:67]
	s_waitcnt lgkmcnt(3)
	v_bfe_u32 v2, v6, 16, 1
	v_add3_u32 v2, v6, v2, s78
	s_waitcnt lgkmcnt(2)
	v_bfe_u32 v3, v18, 16, 1
	ds_read2_b32 v[46:47], v25 offset0:132 offset1:140
	v_lshrrev_b32_e32 v2, 16, v2
	v_add3_u32 v3, v18, v3, s78
	ds_read2_b32 v[48:49], v25 offset0:165 offset1:173
	v_and_or_b32 v2, v3, s79, v2
	s_waitcnt lgkmcnt(3)
	v_bfe_u32 v3, v42, 16, 1
	v_add3_u32 v3, v42, v3, s78
	s_waitcnt lgkmcnt(2)
	v_bfe_u32 v4, v44, 16, 1
	ds_read2_b32 v[50:51], v25 offset0:198 offset1:206
	v_lshrrev_b32_e32 v3, 16, v3
	v_add3_u32 v4, v44, v4, s78
	ds_read2_b32 v[52:53], v25 offset0:231 offset1:239
	v_and_or_b32 v3, v4, s79, v3
	s_waitcnt lgkmcnt(3)
	v_bfe_u32 v4, v46, 16, 1
	v_add3_u32 v4, v46, v4, s78
	s_waitcnt lgkmcnt(2)
	v_bfe_u32 v5, v48, 16, 1
	v_lshrrev_b32_e32 v4, 16, v4
	v_add3_u32 v5, v48, v5, s78
	v_and_or_b32 v4, v5, s79, v4
	s_waitcnt lgkmcnt(1)
	v_bfe_u32 v5, v50, 16, 1
	v_add3_u32 v5, v50, v5, s78
	s_waitcnt lgkmcnt(0)
	v_bfe_u32 v6, v52, 16, 1
	v_lshrrev_b32_e32 v5, 16, v5
	v_add3_u32 v6, v52, v6, s78
	v_and_or_b32 v5, v6, s79, v5
	v_or_b32_e32 v6, s0, v12
	v_lshlrev_b32_e32 v54, 11, v6
	v_mov_b32_e32 v55, v15
	v_lshl_add_u64 v[54:55], v[8:9], 0, v[54:55]
	global_store_dwordx4 v[54:55], v[2:5], off
	v_bfe_u32 v6, v53, 16, 1
	v_add3_u32 v6, v53, v6, s78
	v_bfe_u32 v2, v7, 16, 1
	v_add3_u32 v2, v7, v2, s78
	v_bfe_u32 v3, v19, 16, 1
	v_lshrrev_b32_e32 v2, 16, v2
	v_add3_u32 v3, v19, v3, s78
	v_and_or_b32 v2, v3, s79, v2
	v_bfe_u32 v3, v43, 16, 1
	v_add3_u32 v3, v43, v3, s78
	v_bfe_u32 v4, v45, 16, 1
	v_lshrrev_b32_e32 v3, 16, v3
	v_add3_u32 v4, v45, v4, s78
	v_and_or_b32 v3, v4, s79, v3
	v_bfe_u32 v4, v47, 16, 1
	v_add3_u32 v4, v47, v4, s78
	v_bfe_u32 v5, v49, 16, 1
	v_lshrrev_b32_e32 v4, 16, v4
	v_add3_u32 v5, v49, v5, s78
	v_and_or_b32 v4, v5, s79, v4
	v_bfe_u32 v5, v51, 16, 1
	v_add3_u32 v5, v51, v5, s78
	v_lshrrev_b32_e32 v5, 16, v5
	v_and_or_b32 v5, v6, s79, v5
	v_or_b32_e32 v6, s0, v1
	v_lshlrev_b32_e32 v6, 11, v6
	v_mov_b32_e32 v7, v15
	ds_read2_b32 v[18:19], v25 offset0:16 offset1:24
	v_lshl_add_u64 v[6:7], v[8:9], 0, v[6:7]
	global_store_dwordx4 v[6:7], v[2:5], off
	ds_read2_b32 v[6:7], v25 offset0:49 offset1:57
	ds_read2_b32 v[42:43], v25 offset0:82 offset1:90
	ds_read2_b32 v[44:45], v25 offset0:115 offset1:123
	s_waitcnt lgkmcnt(3)
	v_bfe_u32 v2, v18, 16, 1
	v_add3_u32 v2, v18, v2, s78
	s_waitcnt lgkmcnt(2)
	v_bfe_u32 v3, v6, 16, 1
	ds_read2_b32 v[46:47], v25 offset0:148 offset1:156
	v_lshrrev_b32_e32 v2, 16, v2
	v_add3_u32 v3, v6, v3, s78
	ds_read2_b32 v[48:49], v25 offset0:181 offset1:189
	v_and_or_b32 v2, v3, s79, v2
	s_waitcnt lgkmcnt(3)
	v_bfe_u32 v3, v42, 16, 1
	v_add3_u32 v3, v42, v3, s78
	s_waitcnt lgkmcnt(2)
	v_bfe_u32 v4, v44, 16, 1
	ds_read2_b32 v[50:51], v25 offset0:214 offset1:222
	v_lshrrev_b32_e32 v3, 16, v3
	v_add3_u32 v4, v44, v4, s78
	ds_read2_b32 v[52:53], v25 offset0:247 offset1:255
	v_and_or_b32 v3, v4, s79, v3
	s_waitcnt lgkmcnt(3)
	v_bfe_u32 v4, v46, 16, 1
	v_add3_u32 v4, v46, v4, s78
	s_waitcnt lgkmcnt(2)
	v_bfe_u32 v5, v48, 16, 1
	v_lshrrev_b32_e32 v4, 16, v4
	v_add3_u32 v5, v48, v5, s78
	v_and_or_b32 v4, v5, s79, v4
	s_waitcnt lgkmcnt(1)
	v_bfe_u32 v5, v50, 16, 1
	v_add3_u32 v5, v50, v5, s78
	s_waitcnt lgkmcnt(0)
	v_bfe_u32 v6, v52, 16, 1
	v_lshrrev_b32_e32 v5, 16, v5
	v_add3_u32 v6, v52, v6, s78
	v_and_or_b32 v5, v6, s79, v5
	v_or_b32_e32 v6, s0, v11
	v_lshlrev_b32_e32 v54, 11, v6
	v_mov_b32_e32 v55, v15
	v_lshl_add_u64 v[54:55], v[8:9], 0, v[54:55]
	global_store_dwordx4 v[54:55], v[2:5], off
	v_bfe_u32 v6, v53, 16, 1
	v_add3_u32 v6, v53, v6, s78
	v_bfe_u32 v2, v19, 16, 1
	v_add3_u32 v2, v19, v2, s78
	v_bfe_u32 v3, v7, 16, 1
	v_lshrrev_b32_e32 v2, 16, v2
	v_add3_u32 v3, v7, v3, s78
	v_and_or_b32 v2, v3, s79, v2
	v_bfe_u32 v3, v43, 16, 1
	v_add3_u32 v3, v43, v3, s78
	v_bfe_u32 v4, v45, 16, 1
	v_lshrrev_b32_e32 v3, 16, v3
	v_add3_u32 v4, v45, v4, s78
	v_and_or_b32 v3, v4, s79, v3
	v_bfe_u32 v4, v47, 16, 1
	v_add3_u32 v4, v47, v4, s78
	v_bfe_u32 v5, v49, 16, 1
	v_lshrrev_b32_e32 v4, 16, v4
	v_add3_u32 v5, v49, v5, s78
	v_and_or_b32 v4, v5, s79, v4
	v_bfe_u32 v5, v51, 16, 1
	v_add3_u32 v5, v51, v5, s78
	v_lshrrev_b32_e32 v5, 16, v5
	v_and_or_b32 v5, v6, s79, v5
	v_or_b32_e32 v6, s0, v20
	v_lshlrev_b32_e32 v6, 11, v6
	v_mov_b32_e32 v7, v15
	v_lshl_add_u64 v[6:7], v[8:9], 0, v[6:7]
	global_store_dwordx4 v[6:7], v[2:5], off
	s_waitcnt lgkmcnt(0)

; #define LAS __attribute__((address_space(3)))
; __global__ void __launch_bounds__(NTHREADS, 2) fwd(Args a) {
;     extern __shared__ __attribute__((aligned(16))) unsigned char lds_raw[];
;     LAS unsigned char* lds = (LAS unsigned char*)lds_raw;
;     const int tid = threadIdx.x, lane = tid & 63, wave = __builtin_amdgcn_readfirstlane(tid >> 6);
	.amdhsa_kernel _Z3fwd4Args
		.amdhsa_group_segment_fixed_size 0
		.amdhsa_private_segment_fixed_size 0
		.amdhsa_kernarg_size 416
		.amdhsa_user_sgpr_count 2
		.amdhsa_user_sgpr_dispatch_ptr 0
		.amdhsa_user_sgpr_queue_ptr 0
		.amdhsa_user_sgpr_kernarg_segment_ptr 1
		.amdhsa_user_sgpr_dispatch_id 0
		.amdhsa_user_sgpr_kernarg_preload_length 0
		.amdhsa_user_sgpr_kernarg_preload_offset 0
		.amdhsa_user_sgpr_private_segment_size 0
		.amdhsa_uses_dynamic_stack 0
		.amdhsa_enable_private_segment 0
		.amdhsa_system_sgpr_workgroup_id_x 1
		.amdhsa_system_sgpr_workgroup_id_y 0
		.amdhsa_system_sgpr_workgroup_id_z 0
		.amdhsa_system_sgpr_workgroup_info 0
		.amdhsa_system_vgpr_workitem_id 2
		.amdhsa_next_free_vgpr 248
		.amdhsa_next_free_sgpr 102
		.amdhsa_accum_offset 248
		.amdhsa_reserve_vcc 1
		.amdhsa_float_round_mode_32 0
		.amdhsa_float_round_mode_16_64 0
		.amdhsa_float_denorm_mode_32 3
		.amdhsa_float_denorm_mode_16_64 3
		.amdhsa_dx10_clamp 1
		.amdhsa_ieee_mode 1
		.amdhsa_fp16_overflow 0
		.amdhsa_tg_split 0
		.amdhsa_exception_fp_ieee_invalid_op 0
		.amdhsa_exception_fp_denorm_src 0
		.amdhsa_exception_fp_ieee_div_zero 0
		.amdhsa_exception_fp_ieee_overflow 0
		.amdhsa_exception_fp_ieee_underflow 0
		.amdhsa_exception_fp_ieee_inexact 0
		.amdhsa_exception_int_div_zero 0
	.end_amdhsa_kernel

; #define LAS __attribute__((address_space(3)))
; __global__ void __launch_bounds__(NTHREADS, 2) fwd(Args a) {
;     extern __shared__ __attribute__((aligned(16))) unsigned char lds_raw[];
;     LAS unsigned char* lds = (LAS unsigned char*)lds_raw;
;     const int tid = threadIdx.x, lane = tid & 63, wave = __builtin_amdgcn_readfirstlane(tid >> 6);
amdhsa.kernels:
  - .agpr_count:     0
    .args:
      - .offset:         0
        .size:           160
        .value_kind:     by_value
      - .offset:         160
        .size:           4
        .value_kind:     hidden_block_count_x
      - .offset:         164
        .size:           4
        .value_kind:     hidden_block_count_y
      - .offset:         168
        .size:           4
        .value_kind:     hidden_block_count_z
      - .offset:         172
        .size:           2
        .value_kind:     hidden_group_size_x
      - .offset:         174
        .size:           2
        .value_kind:     hidden_group_size_y
      - .offset:         176
        .size:           2
        .value_kind:     hidden_group_size_z
      - .offset:         178
        .size:           2
        .value_kind:     hidden_remainder_x
      - .offset:         180
        .size:           2
        .value_kind:     hidden_remainder_y
      - .offset:         182
        .size:           2
        .value_kind:     hidden_remainder_z
      - .offset:         200
        .size:           8
        .value_kind:     hidden_global_offset_x
      - .offset:         208
        .size:           8
        .value_kind:     hidden_global_offset_y
      - .offset:         216
        .size:           8
        .value_kind:     hidden_global_offset_z
      - .offset:         224
        .size:           2
        .value_kind:     hidden_grid_dims
      - .offset:         248
        .size:           8
        .value_kind:     hidden_multigrid_sync_arg
      - .offset:         280
        .size:           4
        .value_kind:     hidden_dynamic_lds_size
    .group_segment_fixed_size: 0
    .kernarg_segment_align: 8
    .kernarg_segment_size: 416
    .language:       OpenCL C
    .language_version:
      - 2
      - 0
    .max_flat_workgroup_size: 512
    .name:           _Z3fwd4Args
    .private_segment_fixed_size: 0
    .sgpr_count:     108
    .sgpr_spill_count: 16
    .symbol:         _Z3fwd4Args.kd
    .uniform_work_group_size: 1
    .uses_dynamic_stack: false
    .vgpr_count:     248
    .vgpr_spill_count: 0
    .wavefront_size: 64
